# phase 0 RMS-norm row loop and phase 3 combine loop rewritten with next-trip loads prefetched; combine reductions interleaved
# speedup vs baseline: 1.0440x; 1.0011x over previous
; DI unsigned cvt_pk_bf16(float lo, float hi) { unsigned r; asm("v_cvt_pk_bf16_f32 %0, %1, %2" : "=v"(r) : "v"(lo), "v"(hi)); return r; }
; DI void rms_row2_bf16(const float* __restrict__ x, const float* __restrict__ w, bf16_t* __restrict__ o, int lane) {
;   const float4* xr = (const float4*)x + lane; const float4* wr = (const float4*)w + lane;
;   float4 v[2][4]; float s0 = 0.f, s1 = 0.f;
; #pragma unroll
;   for (int j = 0; j < 4; ++j) { v[0][j] = xr[64 * j]; v[1][j] = xr[256 + 64 * j]; }
; #pragma unroll
;   for (int j = 0; j < 4; ++j) {
;     s0 += v[0][j].x * v[0][j].x + v[0][j].y * v[0][j].y + v[0][j].z * v[0][j].z + v[0][j].w * v[0][j].w;
;     s1 += v[1][j].x * v[1][j].x + v[1][j].y * v[1][j].y + v[1][j].z * v[1][j].z + v[1][j].w * v[1][j].w;
;   }
;   s0 = wave_sum(s0); s1 = wave_sum(s1);
;   const float r0 = rsqrtf(s0 * (1.f / 1024.f) + EPSN), r1 = rsqrtf(s1 * (1.f / 1024.f) + EPSN);
; #pragma unroll
;   for (int j = 0; j < 4; ++j) {
;     const float4 ww = wr[64 * j];
;     uint2 q; q.x = cvt_pk_bf16(v[0][j].x * r0 * ww.x, v[0][j].y * r0 * ww.y); q.y = cvt_pk_bf16(v[0][j].z * r0 * ww.z, v[0][j].w * r0 * ww.w);
;     *(uint2*)(o + lane * 4 + 256 * j) = q;
;     q.x = cvt_pk_bf16(v[1][j].x * r1 * ww.x, v[1][j].y * r1 * ww.y); q.y = cvt_pk_bf16(v[1][j].z * r1 * ww.z, v[1][j].w * r1 * ww.w);
;     *(uint2*)(o + 1024 + lane * 4 + 256 * j) = q;
;   }
; DI void phase_prep(const Params& p) {
;     ...
;   for (int tok = (blockIdx.x * 8 + wave) * 2; tok < NTOK; tok += gridDim.x * 16) rms_row2_bf16(xrow(p, tok), p.attn_norm_w, H + (size_t)tok * 1024, lane);
.LBB0_39:
	s_or_b64 exec, exec, s[0:1]
	v_lshrrev_b32_e32 v0, 5, v202
	v_and_b32_e32 v0, 30, v0
	s_add_u32 s44, s58, 0x2000000
	v_lshl_add_u32 v4, s2, 4, v0
	s_mov_b32 s0, 0x10000
	s_addc_u32 s45, s59, 0
	v_cmp_gt_i32_e32 vcc, s0, v4
	v_mbcnt_lo_u32_b32 v145, -1, 0
	s_and_saveexec_b64 s[4:5], vcc
	s_cbranch_execz .LBB0_42
	v_and_b32_e32 v12, 63, v202
	v_lshlrev_b32_e32 v6, 4, v12
	s_waitcnt lgkmcnt(0)
	global_load_dwordx4 v[0:3], v6, s[64:65]
	v_mbcnt_hi_u32_b32 v5, -1, v145
	v_and_b32_e32 v8, 64, v5
	v_add_u32_e32 v8, 64, v8
	v_xor_b32_e32 v9, 32, v5
	v_cmp_lt_i32_e32 vcc, v9, v8
	v_mov_b32_e32 v7, 0
	s_lshl_b32 s3, s76, 4
	v_cndmask_b32_e32 v9, v5, v9, vcc
	v_lshlrev_b32_e32 v13, 2, v9
	v_xor_b32_e32 v9, 16, v5
	v_cmp_lt_i32_e32 vcc, v9, v8
	s_mov_b64 s[6:7], 0
	s_mov_b32 s9, 0x8000
	v_cndmask_b32_e32 v9, v5, v9, vcc
	v_lshlrev_b32_e32 v14, 2, v9
	v_xor_b32_e32 v9, 8, v5
	v_cmp_lt_i32_e32 vcc, v9, v8
	v_mov_b32_e32 v19, s63
	v_mov_b32_e32 v20, s61
	v_cndmask_b32_e32 v9, v5, v9, vcc
	v_lshlrev_b32_e32 v15, 2, v9
	v_xor_b32_e32 v9, 4, v5
	v_cmp_lt_i32_e32 vcc, v9, v8
	v_mov_b32_e32 v21, s62
	v_mov_b32_e32 v22, s60
	v_cndmask_b32_e32 v9, v5, v9, vcc
	v_lshlrev_b32_e32 v16, 2, v9
	v_xor_b32_e32 v9, 2, v5
	v_cmp_lt_i32_e32 vcc, v9, v8
	s_movk_i32 s10, 0x1000
	s_mov_b32 s8, 0x3a800000
	v_cndmask_b32_e32 v9, v5, v9, vcc
	v_lshlrev_b32_e32 v17, 2, v9
	v_xor_b32_e32 v9, 1, v5
	v_cmp_lt_i32_e32 vcc, v9, v8
	s_mov_b32 s11, 0x800000
	s_mov_b32 s12, 0xffff
	v_cndmask_b32_e32 v5, v5, v9, vcc
	v_lshl_add_u64 v[8:9], s[64:65], 0, v[6:7]
	v_lshlrev_b32_e32 v6, 3, v12
	v_lshlrev_b32_e32 v18, 2, v5
	v_lshl_add_u64 v[10:11], s[44:45], 0, v[6:7]
	v_lshlrev_b32_e32 v6, 4, v12
	v_mov_b32_e32 v12, 0x358637bd
	global_load_dwordx4 v[24:27], v[8:9], off offset:1024
	global_load_dwordx4 v[28:31], v[8:9], off offset:2048
	global_load_dwordx4 v[32:35], v[8:9], off offset:3072
	v_readfirstlane_b32 s98, v4
	v_add_u32_e32 v23, 0xffff8000, v4
	v_ashrrev_i32_e32 v5, 31, v4
	v_cmp_gt_i32_e32 vcc, s9, v4
	v_lshlrev_b64 v[40:41], 11, v[4:5]
	s_nop 1
	v_cndmask_b32_e32 v37, 0, v5, vcc
	v_cndmask_b32_e32 v36, v23, v4, vcc
	v_cndmask_b32_e32 v39, v19, v20, vcc
	v_cndmask_b32_e32 v38, v21, v22, vcc
	v_lshlrev_b64 v[36:37], 12, v[36:37]
	v_lshl_add_u64 v[36:37], v[38:39], 0, v[36:37]
	v_lshl_add_u64 v[52:53], v[36:37], 0, v[6:7]
	v_lshl_add_u64 v[68:69], v[10:11], 0, v[40:41]
	v_add_co_u32_e32 v70, vcc, s10, v52
	s_nop 1
	v_addc_co_u32_e32 v71, vcc, 0, v53, vcc
	global_load_dwordx4 v[76:79], v[52:53], off
	global_load_dwordx4 v[80:83], v[52:53], off offset:1024
	global_load_dwordx4 v[84:87], v[52:53], off offset:2048
	global_load_dwordx4 v[88:91], v[52:53], off offset:3072
	global_load_dwordx4 v[92:95], v[70:71], off
	global_load_dwordx4 v[96:99], v[70:71], off offset:1024
	global_load_dwordx4 v[100:103], v[70:71], off offset:2048
	global_load_dwordx4 v[104:107], v[70:71], off offset:3072
	s_waitcnt vmcnt(0)
	s_branch .Lr0_entry
.Lr0_loop:
	s_waitcnt vmcnt(8)
.Lr0_entry:
	v_mov_b32_e32 v108, v76
	v_mov_b32_e32 v109, v77
	v_mov_b32_e32 v110, v78
	v_mov_b32_e32 v111, v79
	v_mov_b32_e32 v112, v80
	v_mov_b32_e32 v113, v81
	v_mov_b32_e32 v114, v82
	v_mov_b32_e32 v115, v83
	v_mov_b32_e32 v116, v84
	v_mov_b32_e32 v117, v85
	v_mov_b32_e32 v118, v86
	v_mov_b32_e32 v119, v87
	v_mov_b32_e32 v120, v88
	v_mov_b32_e32 v121, v89
	v_mov_b32_e32 v122, v90
	v_mov_b32_e32 v123, v91
	v_mov_b32_e32 v124, v92
	v_mov_b32_e32 v125, v93
	v_mov_b32_e32 v126, v94
	v_mov_b32_e32 v127, v95
	v_mov_b32_e32 v128, v96
	v_mov_b32_e32 v129, v97
	v_mov_b32_e32 v130, v98
	v_mov_b32_e32 v131, v99
	v_mov_b32_e32 v132, v100
	v_mov_b32_e32 v133, v101
	v_mov_b32_e32 v134, v102
	v_mov_b32_e32 v135, v103
	v_mov_b32_e32 v136, v104
	v_mov_b32_e32 v137, v105
	v_mov_b32_e32 v138, v106
	v_mov_b32_e32 v139, v107
	v_mov_b32_e32 v72, v68
	v_mov_b32_e32 v73, v69
	v_add_u32_e32 v4, s3, v4
	s_add_i32 s98, s98, s3
	s_cmp_lt_i32 s98, 0x10000
	s_cbranch_scc0 .Lr0_noload
	v_add_u32_e32 v23, 0xffff8000, v4
	v_ashrrev_i32_e32 v5, 31, v4
	v_cmp_gt_i32_e32 vcc, s9, v4
	v_lshlrev_b64 v[40:41], 11, v[4:5]
	s_nop 1
	v_cndmask_b32_e32 v37, 0, v5, vcc
	v_cndmask_b32_e32 v36, v23, v4, vcc
	v_cndmask_b32_e32 v39, v19, v20, vcc
	v_cndmask_b32_e32 v38, v21, v22, vcc
	v_lshlrev_b64 v[36:37], 12, v[36:37]
	v_lshl_add_u64 v[36:37], v[38:39], 0, v[36:37]
	v_lshl_add_u64 v[52:53], v[36:37], 0, v[6:7]
	v_lshl_add_u64 v[68:69], v[10:11], 0, v[40:41]
	v_add_co_u32_e32 v70, vcc, s10, v52
	s_nop 1
	v_addc_co_u32_e32 v71, vcc, 0, v53, vcc
	global_load_dwordx4 v[76:79], v[52:53], off
	global_load_dwordx4 v[80:83], v[52:53], off offset:1024
	global_load_dwordx4 v[84:87], v[52:53], off offset:2048
	global_load_dwordx4 v[88:91], v[52:53], off offset:3072
	global_load_dwordx4 v[92:95], v[70:71], off
	global_load_dwordx4 v[96:99], v[70:71], off offset:1024
	global_load_dwordx4 v[100:103], v[70:71], off offset:2048
	global_load_dwordx4 v[104:107], v[70:71], off offset:3072
; DI unsigned cvt_pk_bf16(float lo, float hi) { unsigned r; asm("v_cvt_pk_bf16_f32 %0, %1, %2" : "=v"(r) : "v"(lo), "v"(hi)); return r; }
; DI void rms_row2_bf16(const float* __restrict__ x, const float* __restrict__ w, bf16_t* __restrict__ o, int lane) {
;     ...
; #pragma unroll
;   for (int j = 0; j < 4; ++j) {
;     s0 += v[0][j].x * v[0][j].x + v[0][j].y * v[0][j].y + v[0][j].z * v[0][j].z + v[0][j].w * v[0][j].w;
;     s1 += v[1][j].x * v[1][j].x + v[1][j].y * v[1][j].y + v[1][j].z * v[1][j].z + v[1][j].w * v[1][j].w;
;   }
;   s0 = wave_sum(s0); s1 = wave_sum(s1);
;   const float r0 = rsqrtf(s0 * (1.f / 1024.f) + EPSN), r1 = rsqrtf(s1 * (1.f / 1024.f) + EPSN);
; #pragma unroll
;   for (int j = 0; j < 4; ++j) {
;     const float4 ww = wr[64 * j];
;     uint2 q; q.x = cvt_pk_bf16(v[0][j].x * r0 * ww.x, v[0][j].y * r0 * ww.y); q.y = cvt_pk_bf16(v[0][j].z * r0 * ww.z, v[0][j].w * r0 * ww.w);
;     *(uint2*)(o + lane * 4 + 256 * j) = q;
;     q.x = cvt_pk_bf16(v[1][j].x * r1 * ww.x, v[1][j].y * r1 * ww.y); q.y = cvt_pk_bf16(v[1][j].z * r1 * ww.z, v[1][j].w * r1 * ww.w);
;     *(uint2*)(o + 1024 + lane * 4 + 256 * j) = q;
;   }
.Lr0_noload:
	v_mul_f32_e32 v140, v108, v108
	v_fmac_f32_e32 v140, v109, v109
	v_fmac_f32_e32 v140, v110, v110
	v_fmac_f32_e32 v140, v111, v111
	v_fmac_f32_e32 v140, v112, v112
	v_fmac_f32_e32 v140, v113, v113
	v_fmac_f32_e32 v140, v114, v114
	v_fmac_f32_e32 v140, v115, v115
	v_fmac_f32_e32 v140, v116, v116
	v_fmac_f32_e32 v140, v117, v117
	v_fmac_f32_e32 v140, v118, v118
	v_fmac_f32_e32 v140, v119, v119
	v_fmac_f32_e32 v140, v120, v120
	v_fmac_f32_e32 v140, v121, v121
	v_fmac_f32_e32 v140, v122, v122
	v_fmac_f32_e32 v140, v123, v123
	v_mul_f32_e32 v141, v124, v124
	v_fmac_f32_e32 v141, v125, v125
	v_fmac_f32_e32 v141, v126, v126
	v_fmac_f32_e32 v141, v127, v127
	v_fmac_f32_e32 v141, v128, v128
	v_fmac_f32_e32 v141, v129, v129
	v_fmac_f32_e32 v141, v130, v130
	v_fmac_f32_e32 v141, v131, v131
	v_fmac_f32_e32 v141, v132, v132
	v_fmac_f32_e32 v141, v133, v133
	v_fmac_f32_e32 v141, v134, v134
	v_fmac_f32_e32 v141, v135, v135
	v_fmac_f32_e32 v141, v136, v136
	v_fmac_f32_e32 v141, v137, v137
	v_fmac_f32_e32 v141, v138, v138
	v_fmac_f32_e32 v141, v139, v139
	ds_bpermute_b32 v142, v13, v140
	ds_bpermute_b32 v143, v13, v141
	s_waitcnt lgkmcnt(1)
	v_add_f32_e32 v140, v140, v142
	s_waitcnt lgkmcnt(0)
	v_add_f32_e32 v141, v141, v143
	ds_bpermute_b32 v142, v14, v140
	ds_bpermute_b32 v143, v14, v141
	s_waitcnt lgkmcnt(1)
	v_add_f32_e32 v140, v140, v142
	s_waitcnt lgkmcnt(0)
	v_add_f32_e32 v141, v141, v143
	ds_bpermute_b32 v142, v15, v140
	ds_bpermute_b32 v143, v15, v141
	s_waitcnt lgkmcnt(1)
	v_add_f32_e32 v140, v140, v142
	s_waitcnt lgkmcnt(0)
	v_add_f32_e32 v141, v141, v143
	ds_bpermute_b32 v142, v16, v140
	ds_bpermute_b32 v143, v16, v141
	s_waitcnt lgkmcnt(1)
	v_add_f32_e32 v140, v140, v142
	s_waitcnt lgkmcnt(0)
	v_add_f32_e32 v141, v141, v143
	ds_bpermute_b32 v142, v17, v140
	ds_bpermute_b32 v143, v17, v141
	s_waitcnt lgkmcnt(1)
	v_add_f32_e32 v140, v140, v142
	s_waitcnt lgkmcnt(0)
	v_add_f32_e32 v141, v141, v143
	ds_bpermute_b32 v142, v18, v140
	ds_bpermute_b32 v143, v18, v141
	s_waitcnt lgkmcnt(1)
	v_add_f32_e32 v140, v140, v142
	s_waitcnt lgkmcnt(0)
	v_add_f32_e32 v141, v141, v143
	v_fmamk_f32 v140, v140, 0x3a800000, v12
	v_mul_f32_e32 v142, 0x4b800000, v140
	v_cmp_gt_f32_e32 vcc, s11, v140
	s_nop 1
	v_cndmask_b32_e32 v140, v140, v142, vcc
	v_rsq_f32_e32 v140, v140
	s_nop 0
	v_mul_f32_e32 v142, 0x45800000, v140
	v_cndmask_b32_e32 v140, v140, v142, vcc
	v_mul_f32_e32 v146, v108, v140
	v_mul_f32_e32 v147, v109, v140
	v_mul_f32_e32 v148, v110, v140
	v_mul_f32_e32 v149, v111, v140
	v_mul_f32_e32 v146, v146, v0
	v_mul_f32_e32 v147, v147, v1
	v_mul_f32_e32 v148, v148, v2
	v_mul_f32_e32 v149, v149, v3
	v_cvt_pk_bf16_f32 v150, v146, v147
	v_cvt_pk_bf16_f32 v151, v148, v149
	global_store_dwordx2 v[72:73], v[150:151], off
	v_mul_f32_e32 v146, v112, v140
	v_mul_f32_e32 v147, v113, v140
	v_mul_f32_e32 v148, v114, v140
	v_mul_f32_e32 v149, v115, v140
	v_mul_f32_e32 v146, v146, v24
	v_mul_f32_e32 v147, v147, v25
	v_mul_f32_e32 v148, v148, v26
	v_mul_f32_e32 v149, v149, v27
	v_cvt_pk_bf16_f32 v152, v146, v147
	v_cvt_pk_bf16_f32 v153, v148, v149
	global_store_dwordx2 v[72:73], v[152:153], off offset:512
	v_mul_f32_e32 v146, v116, v140
	v_mul_f32_e32 v147, v117, v140
	v_mul_f32_e32 v148, v118, v140
	v_mul_f32_e32 v149, v119, v140
	v_mul_f32_e32 v146, v146, v28
	v_mul_f32_e32 v147, v147, v29
	v_mul_f32_e32 v148, v148, v30
	v_mul_f32_e32 v149, v149, v31
	v_cvt_pk_bf16_f32 v150, v146, v147
	v_cvt_pk_bf16_f32 v151, v148, v149
	global_store_dwordx2 v[72:73], v[150:151], off offset:1024
	v_mul_f32_e32 v146, v120, v140
	v_mul_f32_e32 v147, v121, v140
	v_mul_f32_e32 v148, v122, v140
	v_mul_f32_e32 v149, v123, v140
	v_mul_f32_e32 v146, v146, v32
	v_mul_f32_e32 v147, v147, v33
	v_mul_f32_e32 v148, v148, v34
	v_mul_f32_e32 v149, v149, v35
	v_cvt_pk_bf16_f32 v152, v146, v147
	v_cvt_pk_bf16_f32 v153, v148, v149
	global_store_dwordx2 v[72:73], v[152:153], off offset:1536
	v_fmamk_f32 v141, v141, 0x3a800000, v12
	v_mul_f32_e32 v143, 0x4b800000, v141
	v_cmp_gt_f32_e32 vcc, s11, v141
	s_nop 1
	v_cndmask_b32_e32 v141, v141, v143, vcc
	v_rsq_f32_e32 v141, v141
	s_nop 0
	v_mul_f32_e32 v143, 0x45800000, v141
	v_cndmask_b32_e32 v141, v141, v143, vcc
	v_mul_f32_e32 v146, v124, v141
	v_mul_f32_e32 v147, v125, v141
	v_mul_f32_e32 v148, v126, v141
	v_mul_f32_e32 v149, v127, v141
	v_mul_f32_e32 v146, v146, v0
	v_mul_f32_e32 v147, v147, v1
	v_mul_f32_e32 v148, v148, v2
	v_mul_f32_e32 v149, v149, v3
	v_cvt_pk_bf16_f32 v150, v146, v147
	v_cvt_pk_bf16_f32 v151, v148, v149
	global_store_dwordx2 v[72:73], v[150:151], off offset:2048
	v_mul_f32_e32 v146, v128, v141
	v_mul_f32_e32 v147, v129, v141
	v_mul_f32_e32 v148, v130, v141
	v_mul_f32_e32 v149, v131, v141
	v_mul_f32_e32 v146, v146, v24
	v_mul_f32_e32 v147, v147, v25
	v_mul_f32_e32 v148, v148, v26
	v_mul_f32_e32 v149, v149, v27
	v_cvt_pk_bf16_f32 v152, v146, v147
	v_cvt_pk_bf16_f32 v153, v148, v149
	global_store_dwordx2 v[72:73], v[152:153], off offset:2560
	v_mul_f32_e32 v146, v132, v141
	v_mul_f32_e32 v147, v133, v141
	v_mul_f32_e32 v148, v134, v141
	v_mul_f32_e32 v149, v135, v141
	v_mul_f32_e32 v146, v146, v28
	v_mul_f32_e32 v147, v147, v29
	v_mul_f32_e32 v148, v148, v30
	v_mul_f32_e32 v149, v149, v31
	v_cvt_pk_bf16_f32 v150, v146, v147
	v_cvt_pk_bf16_f32 v151, v148, v149
	global_store_dwordx2 v[72:73], v[150:151], off offset:3072
	v_mul_f32_e32 v146, v136, v141
	v_mul_f32_e32 v147, v137, v141
	v_mul_f32_e32 v148, v138, v141
	v_mul_f32_e32 v149, v139, v141
	v_mul_f32_e32 v146, v146, v32
	v_mul_f32_e32 v147, v147, v33
	v_mul_f32_e32 v148, v148, v34
	v_mul_f32_e32 v149, v149, v35
	v_cvt_pk_bf16_f32 v152, v146, v147
	v_cvt_pk_bf16_f32 v153, v148, v149
	global_store_dwordx2 v[72:73], v[152:153], off offset:3584
	s_cmp_lt_i32 s98, 0x10000
	s_cbranch_scc1 .Lr0_loop

; DI void phase_combine(const Params& p) {
;   const int lane = threadIdx.x & 63, wave = threadIdx.x >> 6;
;   const unsigned* ofw = (const unsigned*)p.out; const unsigned* obw = (const unsigned*)((const bf16_t*)p.out + (size_t)NTOK * 512);
;   const unsigned* GH = (const unsigned*)(p.ws + WS_GH);
;   bf16_t* OC = (bf16_t*)(p.ws + WS_OCAT);
;   const float w0 = p.hgrn_norm_w[lane * 2], w1 = p.hgrn_norm_w[lane * 2 + 1];
;   for (int tok = blockIdx.x * 8 + wave; tok < NTOK; tok += gridDim.x * 8) {
;     unsigned a[4], b[4], g[4];
; #pragma unroll
;     for (int hh = 0; hh < 4; ++hh) { const size_t idx = ((size_t)tok * 512 + hh * 128 + lane * 2) >> 1; a[hh] = ofw[idx]; b[hh] = obw[idx]; g[hh] = GH[idx]; }
.LBB0_1061:
	s_or_b64 exec, exec, s[0:1]
	s_waitcnt lgkmcnt(0)
	v_lshrrev_b32_e32 v0, 6, v202
	v_lshl_add_u32 v0, s2, 3, v0
	s_mov_b32 s0, 0x10000
	v_cmp_gt_i32_e32 vcc, s0, v0
	s_barrier
	s_and_saveexec_b64 s[4:5], vcc
	s_cbranch_execz .LBB0_1064
	v_and_b32_e32 v4, 0x7e, v203
	v_lshlrev_b32_e32 v1, 2, v4
	global_load_dwordx2 v[2:3], v1, s[46:47]
	v_cmp_lt_i32_e32 vcc, v206, v205
	s_add_u32 s6, s56, 0x4000000
	s_addc_u32 s7, s57, 0
	v_cndmask_b32_e32 v1, v204, v206, vcc
	v_cmp_lt_i32_e32 vcc, v207, v205
	v_lshlrev_b32_e32 v8, 2, v1
	s_add_u32 s8, s58, 0x26000000
	v_cndmask_b32_e32 v1, v204, v207, vcc
	v_cmp_lt_i32_e32 vcc, v211, v205
	v_lshlrev_b32_e32 v9, 2, v1
	s_addc_u32 s9, s59, 0
	v_cndmask_b32_e32 v1, v204, v211, vcc
	v_cmp_lt_i32_e32 vcc, v210, v205
	v_lshlrev_b32_e32 v10, 2, v1
	v_mov_b32_e32 v5, 0
	v_cndmask_b32_e32 v1, v204, v210, vcc
	v_cmp_lt_i32_e32 vcc, v209, v205
	v_lshlrev_b32_e32 v11, 2, v1
	s_lshl_b32 s3, s76, 3
	v_cndmask_b32_e32 v1, v204, v209, vcc
	v_cmp_lt_i32_e32 vcc, v208, v205
	v_lshlrev_b32_e32 v12, 2, v1
	s_mov_b64 s[10:11], 0
	v_cndmask_b32_e32 v1, v204, v208, vcc
	v_lshlrev_b32_e32 v13, 2, v1
	v_lshlrev_b32_e32 v4, 1, v4
	s_mov_b64 s[12:13], 0x2a000400
	v_mov_b32_e32 v14, 0x358637bd
	s_mov_b32 s14, 0x800000
	s_mov_b32 s15, 0x2a000000
	s_mov_b32 s16, 0xffff
	v_readfirstlane_b32 s98, v0
	v_ashrrev_i32_e32 v1, 31, v0
	v_lshlrev_b64 v[90:91], 10, v[0:1]
	v_or_b32_e32 v90, v90, v4
	v_lshl_add_u64 v[92:93], s[56:57], 0, v[90:91]
	v_lshl_add_u64 v[94:95], s[6:7], 0, v[90:91]
	v_lshl_add_u64 v[96:97], s[8:9], 0, v[90:91]
	global_load_dword v40, v[92:93], off
	global_load_dword v41, v[92:93], off offset:256
	global_load_dword v42, v[92:93], off offset:512
	global_load_dword v43, v[92:93], off offset:768
	global_load_dword v44, v[94:95], off
	global_load_dword v45, v[94:95], off offset:256
	global_load_dword v46, v[94:95], off offset:512
	global_load_dword v47, v[94:95], off offset:768
	global_load_dword v48, v[96:97], off
	global_load_dword v49, v[96:97], off offset:256
	global_load_dword v50, v[96:97], off offset:512
	global_load_dword v51, v[96:97], off offset:768
	s_waitcnt vmcnt(0)
	s_branch .Lc3_entry

; DI unsigned cvt_pk_bf16(float lo, float hi) { unsigned r; asm("v_cvt_pk_bf16_f32 %0, %1, %2" : "=v"(r) : "v"(lo), "v"(hi)); return r; }
; DI void phase_combine(const Params& p) {
;     ...
;   for (int tok = blockIdx.x * 8 + wave; tok < NTOK; tok += gridDim.x * 8) {
;     unsigned a[4], b[4], g[4];
; #pragma unroll
;     for (int hh = 0; hh < 4; ++hh) { const size_t idx = ((size_t)tok * 512 + hh * 128 + lane * 2) >> 1; a[hh] = ofw[idx]; b[hh] = obw[idx]; g[hh] = GH[idx]; }
; #pragma unroll
;     for (int hh = 0; hh < 4; ++hh) {
;       const float o0 = __uint_as_float(a[hh] << 16) + __uint_as_float(b[hh] << 16), o1 = __uint_as_float(a[hh] & 0xffff0000u) + __uint_as_float(b[hh] & 0xffff0000u);
;       const float ss = wave_sum(o0 * o0 + o1 * o1);
;       const float rstd = rsqrtf(ss * (1.f / 128.f) + EPSN);
;       const float g0 = __uint_as_float(g[hh] << 16), g1 = __uint_as_float(g[hh] & 0xffff0000u);
;       *(unsigned*)(OC + (size_t)tok * 1024 + 512 + hh * 128 + lane * 2) = cvt_pk_bf16(o0 * rstd * w0 * g0, o1 * rstd * w1 * g1);
;     }
;   }
.Lc3_entry:
	v_mov_b32_e32 v52, v40
	v_mov_b32_e32 v53, v41
	v_mov_b32_e32 v54, v42
	v_mov_b32_e32 v55, v43
	v_mov_b32_e32 v56, v44
	v_mov_b32_e32 v57, v45
	v_mov_b32_e32 v58, v46
	v_mov_b32_e32 v59, v47
	v_mov_b32_e32 v60, v48
	v_mov_b32_e32 v61, v49
	v_mov_b32_e32 v62, v50
	v_mov_b32_e32 v63, v51
	v_mov_b32_e32 v100, v0
	v_add_u32_e32 v0, s3, v0
	s_add_i32 s98, s98, s3
	s_cmp_lt_i32 s98, 0x10000
	s_cbranch_scc0 .Lc3_noload
	v_ashrrev_i32_e32 v1, 31, v0
	v_lshlrev_b64 v[90:91], 10, v[0:1]
	v_or_b32_e32 v90, v90, v4
	v_lshl_add_u64 v[92:93], s[56:57], 0, v[90:91]
	v_lshl_add_u64 v[94:95], s[6:7], 0, v[90:91]
	v_lshl_add_u64 v[96:97], s[8:9], 0, v[90:91]
	global_load_dword v40, v[92:93], off
	global_load_dword v41, v[92:93], off offset:256
	global_load_dword v42, v[92:93], off offset:512
	global_load_dword v43, v[92:93], off offset:768
	global_load_dword v44, v[94:95], off
	global_load_dword v45, v[94:95], off offset:256
	global_load_dword v46, v[94:95], off offset:512
	global_load_dword v47, v[94:95], off offset:768
	global_load_dword v48, v[96:97], off
	global_load_dword v49, v[96:97], off offset:256
	global_load_dword v50, v[96:97], off offset:512
	global_load_dword v51, v[96:97], off offset:768
.Lc3_noload:
	v_lshlrev_b32_e32 v64, 16, v52
	v_lshlrev_b32_e32 v76, 16, v56
	v_and_b32_e32 v68, 0xffff0000, v52
	v_and_b32_e32 v80, 0xffff0000, v56
	v_add_f32_e32 v64, v64, v76
	v_add_f32_e32 v68, v68, v80
	v_mul_f32_e32 v72, v64, v64
	v_mul_f32_e32 v76, v68, v68
	v_add_f32_e32 v72, v72, v76
	v_lshlrev_b32_e32 v65, 16, v53
	v_lshlrev_b32_e32 v77, 16, v57
	v_and_b32_e32 v69, 0xffff0000, v53
	v_and_b32_e32 v81, 0xffff0000, v57
	v_add_f32_e32 v65, v65, v77
	v_add_f32_e32 v69, v69, v81
	v_mul_f32_e32 v73, v65, v65
	v_mul_f32_e32 v77, v69, v69
	v_add_f32_e32 v73, v73, v77
	v_lshlrev_b32_e32 v66, 16, v54
	v_lshlrev_b32_e32 v78, 16, v58
	v_and_b32_e32 v70, 0xffff0000, v54
	v_and_b32_e32 v82, 0xffff0000, v58
	v_add_f32_e32 v66, v66, v78
	v_add_f32_e32 v70, v70, v82
	v_mul_f32_e32 v74, v66, v66
	v_mul_f32_e32 v78, v70, v70
	v_add_f32_e32 v74, v74, v78
	v_lshlrev_b32_e32 v67, 16, v55
	v_lshlrev_b32_e32 v79, 16, v59
	v_and_b32_e32 v71, 0xffff0000, v55
	v_and_b32_e32 v83, 0xffff0000, v59
	v_add_f32_e32 v67, v67, v79
	v_add_f32_e32 v71, v71, v83
	v_mul_f32_e32 v75, v67, v67
	v_mul_f32_e32 v79, v71, v71
	v_add_f32_e32 v75, v75, v79
	v_ashrrev_i32_e32 v101, 31, v100
	v_lshlrev_b64 v[98:99], 11, v[100:101]
	v_lshl_add_u64 v[98:99], s[58:59], 0, v[98:99]
	v_lshl_add_u64 v[98:99], v[98:99], 0, v[4:5]
	v_lshl_add_u64 v[98:99], v[98:99], 0, s[12:13]
	ds_bpermute_b32 v76, v8, v72
	ds_bpermute_b32 v77, v8, v73
	ds_bpermute_b32 v78, v8, v74
	ds_bpermute_b32 v79, v8, v75
	s_waitcnt lgkmcnt(3)
	v_add_f32_e32 v72, v72, v76
	s_waitcnt lgkmcnt(2)
	v_add_f32_e32 v73, v73, v77
	s_waitcnt lgkmcnt(1)
	v_add_f32_e32 v74, v74, v78
	s_waitcnt lgkmcnt(0)
	v_add_f32_e32 v75, v75, v79
	ds_bpermute_b32 v76, v9, v72
	ds_bpermute_b32 v77, v9, v73
	ds_bpermute_b32 v78, v9, v74
	ds_bpermute_b32 v79, v9, v75
	s_waitcnt lgkmcnt(3)
	v_add_f32_e32 v72, v72, v76
	s_waitcnt lgkmcnt(2)
	v_add_f32_e32 v73, v73, v77
	s_waitcnt lgkmcnt(1)
	v_add_f32_e32 v74, v74, v78
	s_waitcnt lgkmcnt(0)
	v_add_f32_e32 v75, v75, v79
	ds_bpermute_b32 v76, v10, v72
	ds_bpermute_b32 v77, v10, v73
	ds_bpermute_b32 v78, v10, v74
	ds_bpermute_b32 v79, v10, v75
	s_waitcnt lgkmcnt(3)
	v_add_f32_e32 v72, v72, v76
	s_waitcnt lgkmcnt(2)
	v_add_f32_e32 v73, v73, v77
	s_waitcnt lgkmcnt(1)
	v_add_f32_e32 v74, v74, v78
	s_waitcnt lgkmcnt(0)
	v_add_f32_e32 v75, v75, v79
	ds_bpermute_b32 v76, v11, v72
	ds_bpermute_b32 v77, v11, v73
	ds_bpermute_b32 v78, v11, v74
	ds_bpermute_b32 v79, v11, v75
	s_waitcnt lgkmcnt(3)
	v_add_f32_e32 v72, v72, v76
	s_waitcnt lgkmcnt(2)
	v_add_f32_e32 v73, v73, v77
	s_waitcnt lgkmcnt(1)
	v_add_f32_e32 v74, v74, v78
	s_waitcnt lgkmcnt(0)
	v_add_f32_e32 v75, v75, v79
	ds_bpermute_b32 v76, v12, v72
	ds_bpermute_b32 v77, v12, v73
	ds_bpermute_b32 v78, v12, v74
	ds_bpermute_b32 v79, v12, v75
	s_waitcnt lgkmcnt(3)
	v_add_f32_e32 v72, v72, v76
	s_waitcnt lgkmcnt(2)
	v_add_f32_e32 v73, v73, v77
	s_waitcnt lgkmcnt(1)
	v_add_f32_e32 v74, v74, v78
	s_waitcnt lgkmcnt(0)
	v_add_f32_e32 v75, v75, v79
	ds_bpermute_b32 v76, v13, v72
	ds_bpermute_b32 v77, v13, v73
	ds_bpermute_b32 v78, v13, v74
	ds_bpermute_b32 v79, v13, v75
	s_waitcnt lgkmcnt(3)
	v_add_f32_e32 v72, v72, v76
	s_waitcnt lgkmcnt(2)
	v_add_f32_e32 v73, v73, v77
	s_waitcnt lgkmcnt(1)
	v_add_f32_e32 v74, v74, v78
	s_waitcnt lgkmcnt(0)
	v_add_f32_e32 v75, v75, v79
	v_fmamk_f32 v80, v72, 0x3c000000, v14
	v_mul_f32_e32 v76, 0x4b800000, v80
	v_cmp_gt_f32_e32 vcc, s14, v80
	s_nop 1
	v_cndmask_b32_e32 v80, v80, v76, vcc
	v_rsq_f32_e32 v80, v80
	s_nop 0
	v_mul_f32_e32 v76, 0x45800000, v80
	v_cndmask_b32_e32 v80, v80, v76, vcc
	v_mul_f32_e32 v64, v64, v80
	v_mul_f32_e32 v68, v68, v80
	v_mul_f32_e32 v64, v2, v64
	v_mul_f32_e32 v68, v3, v68
	v_lshlrev_b32_e32 v76, 16, v60
	v_and_b32_e32 v72, 0xffff0000, v60
	v_mul_f32_e32 v64, v64, v76
	v_mul_f32_e32 v68, v68, v72
	v_cvt_pk_bf16_f32 v64, v64, v68
	global_store_dword v[98:99], v64, off
	v_fmamk_f32 v81, v73, 0x3c000000, v14
	v_mul_f32_e32 v77, 0x4b800000, v81
	v_cmp_gt_f32_e32 vcc, s14, v81
	s_nop 1
	v_cndmask_b32_e32 v81, v81, v77, vcc
	v_rsq_f32_e32 v81, v81
	s_nop 0
	v_mul_f32_e32 v77, 0x45800000, v81
	v_cndmask_b32_e32 v81, v81, v77, vcc
	v_mul_f32_e32 v65, v65, v81
	v_mul_f32_e32 v69, v69, v81
	v_mul_f32_e32 v65, v2, v65
	v_mul_f32_e32 v69, v3, v69
	v_lshlrev_b32_e32 v77, 16, v61
	v_and_b32_e32 v73, 0xffff0000, v61
	v_mul_f32_e32 v65, v65, v77
	v_mul_f32_e32 v69, v69, v73
	v_cvt_pk_bf16_f32 v65, v65, v69
	global_store_dword v[98:99], v65, off offset:256
	v_fmamk_f32 v82, v74, 0x3c000000, v14
	v_mul_f32_e32 v78, 0x4b800000, v82
	v_cmp_gt_f32_e32 vcc, s14, v82
	s_nop 1
	v_cndmask_b32_e32 v82, v82, v78, vcc
	v_rsq_f32_e32 v82, v82
	s_nop 0
	v_mul_f32_e32 v78, 0x45800000, v82
	v_cndmask_b32_e32 v82, v82, v78, vcc
	v_mul_f32_e32 v66, v66, v82
	v_mul_f32_e32 v70, v70, v82
	v_mul_f32_e32 v66, v2, v66
	v_mul_f32_e32 v70, v3, v70
	v_lshlrev_b32_e32 v78, 16, v62
	v_and_b32_e32 v74, 0xffff0000, v62
	v_mul_f32_e32 v66, v66, v78
	v_mul_f32_e32 v70, v70, v74
	v_cvt_pk_bf16_f32 v66, v66, v70
	global_store_dword v[98:99], v66, off offset:512
	v_fmamk_f32 v83, v75, 0x3c000000, v14
	v_mul_f32_e32 v79, 0x4b800000, v83
	v_cmp_gt_f32_e32 vcc, s14, v83
	s_nop 1
	v_cndmask_b32_e32 v83, v83, v79, vcc
	v_rsq_f32_e32 v83, v83
	s_nop 0
	v_mul_f32_e32 v79, 0x45800000, v83
	v_cndmask_b32_e32 v83, v83, v79, vcc
	v_mul_f32_e32 v67, v67, v83
	v_mul_f32_e32 v71, v71, v83
	v_mul_f32_e32 v67, v2, v67
	v_mul_f32_e32 v71, v3, v71
	v_lshlrev_b32_e32 v79, 16, v63
	v_and_b32_e32 v75, 0xffff0000, v63
	v_mul_f32_e32 v67, v67, v79
	v_mul_f32_e32 v71, v71, v75
	v_cvt_pk_bf16_f32 v67, v67, v71
	global_store_dword v[98:99], v67, off offset:768
	s_cmp_lt_i32 s98, 0x10000
	s_cbranch_scc1 .Lc3_loop
